# within-XCD stagger of GEMM workers ((bx>>3)&3)*d by s_sleep in P2 and P8 so one XCD's epilogue stores fit its L2
# speedup vs baseline: 1.0129x; 1.0129x over previous
.LBB0_210:
	s_and_b64 vcc, exec, s[0:1]
	s_cbranch_vccz .LBB0_552
	s_cmpk_lt_i32 s92, 0x420
	s_cselect_b64 s[0:1], -1, 0
	s_cmpk_gt_i32 s92, 0x41f
	v_readfirstlane_b32 s2, v0
	s_cbranch_scc1 .LBB0_213
	s_lshr_b32 s3, s92, 3
	s_and_b32 s3, s3, 3
	s_cmp_eq_u32 s3, 0
	s_cbranch_scc1 .Lstag_done_P2

.LBB0_2131:
	s_and_b64 vcc, exec, s[4:5]
	s_cbranch_vccz .LBB0_2148
	s_cmpk_gt_i32 s92, 0x20f
	v_readfirstlane_b32 s0, v0
	s_cbranch_scc1 .LBB0_2148
	s_lshr_b32 s4, s92, 3
	s_and_b32 s4, s4, 3
	s_cmp_eq_u32 s4, 0
	s_cbranch_scc1 .Lstag_done_P8
